# GEMM K-loop: each phase's LDS-DMA stage loads issued at the head of the load segment, ahead of the ds_reads
# baseline (speedup 1.0000x reference)
.LBB0_141:
	v_lshl_add_u64 v[176:177], s[0:1], 0, v[192:193]
	s_add_i32 m0, s76, 0xc000
	s_nop 0
	global_load_lds_dwordx4 v[176:177], off
	v_lshl_add_u64 v[176:177], s[0:1], 0, v[194:195]
	s_add_i32 m0, s76, 0xe000
	s_nop 0
	global_load_lds_dwordx4 v[176:177], off
	s_add_i32 s72, s40, 2
	s_add_u32 s68, s0, 0x80
	s_addc_u32 s41, s1, 0
	s_add_i32 s73, 0, 0x10000
	v_add_u32_e32 v140, s73, v183
	ds_read_b128 v[128:131], v140
	ds_read_b128 v[132:135], v140 offset:1024
	ds_read_b128 v[136:139], v140 offset:2048
	ds_read_b128 v[140:143], v140 offset:3072
	s_cmp_eq_u32 s10, s40
	s_cselect_b32 s40, s64, s68
	s_cselect_b32 s41, s65, s41
	s_cselect_b32 s69, s67, s71
	s_cselect_b32 s68, s66, s70
	ds_read_b128 v[144:147], v239
	ds_read_b128 v[148:151], v239 offset:1024
	ds_read_b128 v[152:155], v239 offset:2048
	ds_read_b128 v[156:159], v239 offset:3072
	ds_read_b128 v[160:163], v239 offset:4096
	ds_read_b128 v[164:167], v239 offset:5120
	ds_read_b128 v[168:171], v239 offset:6144
	ds_read_b128 v[172:175], v239 offset:7168
	s_waitcnt lgkmcnt(8)
	s_barrier
	s_waitcnt lgkmcnt(0)
	s_waitcnt lgkmcnt(0)
	v_mfma_f32_16x16x32_bf16 v[124:127], v[128:131], v[144:147], v[124:127]
	v_mfma_f32_16x16x32_bf16 v[116:119], v[136:139], v[144:147], v[116:119]
	v_mfma_f32_16x16x32_bf16 v[108:111], v[128:131], v[152:155], v[108:111]
	v_mfma_f32_16x16x32_bf16 v[100:103], v[136:139], v[152:155], v[100:103]
	v_mfma_f32_16x16x32_bf16 v[92:95], v[128:131], v[160:163], v[92:95]
	v_mfma_f32_16x16x32_bf16 v[84:87], v[136:139], v[160:163], v[84:87]
	v_mfma_f32_16x16x32_bf16 v[76:79], v[128:131], v[168:171], v[76:79]
	v_mfma_f32_16x16x32_bf16 v[68:71], v[136:139], v[168:171], v[68:71]
	v_mfma_f32_16x16x32_bf16 v[124:127], v[132:135], v[148:151], v[124:127]
	v_mfma_f32_16x16x32_bf16 v[116:119], v[140:143], v[148:151], v[116:119]
	v_mfma_f32_16x16x32_bf16 v[108:111], v[132:135], v[156:159], v[108:111]
	v_mfma_f32_16x16x32_bf16 v[100:103], v[140:143], v[156:159], v[100:103]
	v_mfma_f32_16x16x32_bf16 v[92:95], v[132:135], v[164:167], v[92:95]
	v_mfma_f32_16x16x32_bf16 v[84:87], v[140:143], v[164:167], v[84:87]
	v_mfma_f32_16x16x32_bf16 v[76:79], v[132:135], v[172:175], v[76:79]
	v_mfma_f32_16x16x32_bf16 v[68:71], v[140:143], v[172:175], v[68:71]
	s_barrier
	s_add_i32 s80, 0, 0x14000
	s_add_i32 s73, s73, s33
	v_lshl_add_u64 v[208:209], s[68:69], 0, v[186:187]
	s_mov_b32 m0, s73
	s_nop 0
	global_load_lds_dwordx4 v[208:209], off
	v_lshl_add_u64 v[210:211], s[68:69], 0, v[190:191]
	s_add_i32 m0, s73, 0x2000
	s_nop 0
	global_load_lds_dwordx4 v[210:211], off
	v_add_u32_e32 v204, s80, v183
	ds_read_b128 v[176:179], v204
	ds_read_b128 v[196:199], v204 offset:1024
	ds_read_b128 v[200:203], v204 offset:2048
	ds_read_b128 v[204:207], v204 offset:3072
	s_barrier
	s_waitcnt lgkmcnt(0)
	s_waitcnt lgkmcnt(0)
	v_mfma_f32_16x16x32_bf16 v[120:123], v[176:179], v[144:147], v[120:123]
	v_mfma_f32_16x16x32_bf16 v[112:115], v[200:203], v[144:147], v[112:115]
	v_mfma_f32_16x16x32_bf16 v[104:107], v[176:179], v[152:155], v[104:107]
	v_mfma_f32_16x16x32_bf16 v[96:99], v[200:203], v[152:155], v[96:99]
	v_mfma_f32_16x16x32_bf16 v[88:91], v[176:179], v[160:163], v[88:91]
	v_mfma_f32_16x16x32_bf16 v[80:83], v[200:203], v[160:163], v[80:83]
	v_mfma_f32_16x16x32_bf16 v[72:75], v[176:179], v[168:171], v[72:75]
	v_mfma_f32_16x16x32_bf16 v[64:67], v[200:203], v[168:171], v[64:67]
	v_mfma_f32_16x16x32_bf16 v[120:123], v[196:199], v[148:151], v[120:123]
	v_mfma_f32_16x16x32_bf16 v[112:115], v[204:207], v[148:151], v[112:115]
	v_mfma_f32_16x16x32_bf16 v[104:107], v[196:199], v[156:159], v[104:107]
	v_mfma_f32_16x16x32_bf16 v[96:99], v[204:207], v[156:159], v[96:99]
	v_mfma_f32_16x16x32_bf16 v[88:91], v[196:199], v[164:167], v[88:91]
	v_mfma_f32_16x16x32_bf16 v[80:83], v[204:207], v[164:167], v[80:83]
	v_mfma_f32_16x16x32_bf16 v[72:75], v[196:199], v[172:175], v[72:75]
	v_mfma_f32_16x16x32_bf16 v[64:67], v[204:207], v[172:175], v[64:67]
	s_mov_b32 m0, s76
	v_lshl_add_u64 v[212:213], s[40:41], 0, v[184:185]
	s_barrier
	global_load_lds_dwordx4 v[212:213], off
	v_lshl_add_u64 v[214:215], s[40:41], 0, v[188:189]
	s_mov_b32 m0, s4
	s_nop 0
	global_load_lds_dwordx4 v[214:215], off
	ds_read_b128 v[144:147], v239 offset:16384
	ds_read_b128 v[148:151], v239 offset:17408
	ds_read_b128 v[152:155], v239 offset:18432
	ds_read_b128 v[156:159], v239 offset:19456
	ds_read_b128 v[160:163], v239 offset:20480
	ds_read_b128 v[164:167], v239 offset:21504
	ds_read_b128 v[168:171], v239 offset:22528
	ds_read_b128 v[172:175], v239 offset:23552
	s_barrier
	s_waitcnt lgkmcnt(0)
	s_waitcnt lgkmcnt(0)
	v_mfma_f32_16x16x32_bf16 v[60:63], v[128:131], v[144:147], v[60:63]
	v_mfma_f32_16x16x32_bf16 v[52:55], v[136:139], v[144:147], v[52:55]
	v_mfma_f32_16x16x32_bf16 v[44:47], v[128:131], v[152:155], v[44:47]
	v_mfma_f32_16x16x32_bf16 v[36:39], v[136:139], v[152:155], v[36:39]
	v_mfma_f32_16x16x32_bf16 v[28:31], v[128:131], v[160:163], v[28:31]
	v_mfma_f32_16x16x32_bf16 v[20:23], v[136:139], v[160:163], v[20:23]
	v_mfma_f32_16x16x32_bf16 v[12:15], v[128:131], v[168:171], v[12:15]
	v_mfma_f32_16x16x32_bf16 v[4:7], v[136:139], v[168:171], v[4:7]
	v_mfma_f32_16x16x32_bf16 v[60:63], v[132:135], v[148:151], v[60:63]
	v_mfma_f32_16x16x32_bf16 v[52:55], v[140:143], v[148:151], v[52:55]
	v_mfma_f32_16x16x32_bf16 v[44:47], v[132:135], v[156:159], v[44:47]
	v_mfma_f32_16x16x32_bf16 v[36:39], v[140:143], v[156:159], v[36:39]
	v_mfma_f32_16x16x32_bf16 v[28:31], v[132:135], v[164:167], v[28:31]
	v_mfma_f32_16x16x32_bf16 v[20:23], v[140:143], v[164:167], v[20:23]
	v_mfma_f32_16x16x32_bf16 v[12:15], v[132:135], v[172:175], v[12:15]
	v_mfma_f32_16x16x32_bf16 v[4:7], v[140:143], v[172:175], v[4:7]
	s_barrier
	s_add_u32 s68, s68, s98
	s_addc_u32 s69, s69, 0
	s_add_i32 s73, s80, s33
	v_lshl_add_u64 v[216:217], s[68:69], 0, v[186:187]
	s_mov_b32 m0, s73
	s_nop 0
	global_load_lds_dwordx4 v[216:217], off
	v_lshl_add_u64 v[218:219], s[68:69], 0, v[190:191]
	s_add_i32 m0, s73, 0x2000
	s_nop 0
	global_load_lds_dwordx4 v[218:219], off
	s_waitcnt vmcnt(6)
	s_barrier
	v_mfma_f32_16x16x32_bf16 v[56:59], v[176:179], v[144:147], v[56:59]
	v_mfma_f32_16x16x32_bf16 v[48:51], v[200:203], v[144:147], v[48:51]
	v_mfma_f32_16x16x32_bf16 v[40:43], v[176:179], v[152:155], v[40:43]
	v_mfma_f32_16x16x32_bf16 v[32:35], v[200:203], v[152:155], v[32:35]
	v_mfma_f32_16x16x32_bf16 v[24:27], v[176:179], v[160:163], v[24:27]
	v_mfma_f32_16x16x32_bf16 v[16:19], v[200:203], v[160:163], v[16:19]
	v_mfma_f32_16x16x32_bf16 v[8:11], v[176:179], v[168:171], v[8:11]
	v_mfma_f32_16x16x32_bf16 v[0:3], v[200:203], v[168:171], v[0:3]
	v_mfma_f32_16x16x32_bf16 v[56:59], v[196:199], v[148:151], v[56:59]
	v_mfma_f32_16x16x32_bf16 v[48:51], v[204:207], v[148:151], v[48:51]
	v_mfma_f32_16x16x32_bf16 v[40:43], v[196:199], v[156:159], v[40:43]
	v_mfma_f32_16x16x32_bf16 v[32:35], v[204:207], v[156:159], v[32:35]
	v_mfma_f32_16x16x32_bf16 v[24:27], v[196:199], v[164:167], v[24:27]
	v_mfma_f32_16x16x32_bf16 v[16:19], v[204:207], v[164:167], v[16:19]
	v_mfma_f32_16x16x32_bf16 v[8:11], v[196:199], v[172:175], v[8:11]
	v_mfma_f32_16x16x32_bf16 v[0:3], v[204:207], v[172:175], v[0:3]
	s_add_i32 s68, 0, 0x18000
	v_add_u32_e32 v140, s68, v183
	s_barrier
	ds_read_b128 v[128:131], v140
	ds_read_b128 v[132:135], v140 offset:1024
	ds_read_b128 v[136:139], v140 offset:2048
	ds_read_b128 v[140:143], v140 offset:3072
	s_add_u32 s40, s40, s98
	s_addc_u32 s41, s41, 0
	s_mov_b32 m0, s5
	v_lshl_add_u64 v[176:177], s[40:41], 0, v[184:185]
	s_nop 0
	global_load_lds_dwordx4 v[176:177], off
	v_lshl_add_u64 v[176:177], s[40:41], 0, v[188:189]
	s_mov_b32 m0, s6
	s_nop 0
	global_load_lds_dwordx4 v[176:177], off
	ds_read_b128 v[144:147], v239 offset:32768
	ds_read_b128 v[148:151], v239 offset:33792
	ds_read_b128 v[152:155], v239 offset:34816
	ds_read_b128 v[156:159], v239 offset:35840
	ds_read_b128 v[160:163], v239 offset:36864
	ds_read_b128 v[164:167], v239 offset:37888
	ds_read_b128 v[168:171], v239 offset:38912
	ds_read_b128 v[172:175], v239 offset:39936
	s_waitcnt lgkmcnt(8)
	s_barrier
	s_waitcnt lgkmcnt(0)
	s_waitcnt lgkmcnt(0)
	v_mfma_f32_16x16x32_bf16 v[124:127], v[128:131], v[144:147], v[124:127]
	v_mfma_f32_16x16x32_bf16 v[116:119], v[136:139], v[144:147], v[116:119]
	v_mfma_f32_16x16x32_bf16 v[108:111], v[128:131], v[152:155], v[108:111]
	v_mfma_f32_16x16x32_bf16 v[100:103], v[136:139], v[152:155], v[100:103]
	v_mfma_f32_16x16x32_bf16 v[92:95], v[128:131], v[160:163], v[92:95]
	v_mfma_f32_16x16x32_bf16 v[84:87], v[136:139], v[160:163], v[84:87]
	v_mfma_f32_16x16x32_bf16 v[76:79], v[128:131], v[168:171], v[76:79]
	v_mfma_f32_16x16x32_bf16 v[68:71], v[136:139], v[168:171], v[68:71]
	v_mfma_f32_16x16x32_bf16 v[124:127], v[132:135], v[148:151], v[124:127]
	v_mfma_f32_16x16x32_bf16 v[116:119], v[140:143], v[148:151], v[116:119]
	v_mfma_f32_16x16x32_bf16 v[108:111], v[132:135], v[156:159], v[108:111]
	v_mfma_f32_16x16x32_bf16 v[100:103], v[140:143], v[156:159], v[100:103]
	v_mfma_f32_16x16x32_bf16 v[92:95], v[132:135], v[164:167], v[92:95]
	v_mfma_f32_16x16x32_bf16 v[84:87], v[140:143], v[164:167], v[84:87]
	v_mfma_f32_16x16x32_bf16 v[76:79], v[132:135], v[172:175], v[76:79]
	v_mfma_f32_16x16x32_bf16 v[68:71], v[140:143], v[172:175], v[68:71]
	s_barrier
	s_add_i32 s40, 0, 0x1c000
	s_add_i32 s41, s68, s33
	v_lshl_add_u64 v[208:209], v[208:209], 0, s[96:97]
	s_mov_b32 m0, s41
	s_nop 0
	global_load_lds_dwordx4 v[208:209], off
	v_lshl_add_u64 v[208:209], v[210:211], 0, s[96:97]
	s_add_i32 m0, s41, 0x2000
	s_nop 0
	global_load_lds_dwordx4 v[208:209], off
	v_add_u32_e32 v204, s40, v183
	ds_read_b128 v[176:179], v204
	ds_read_b128 v[196:199], v204 offset:1024
	ds_read_b128 v[200:203], v204 offset:2048
	ds_read_b128 v[204:207], v204 offset:3072
	s_barrier
	s_waitcnt lgkmcnt(0)
	s_waitcnt lgkmcnt(0)
	v_mfma_f32_16x16x32_bf16 v[120:123], v[176:179], v[144:147], v[120:123]
	v_mfma_f32_16x16x32_bf16 v[112:115], v[200:203], v[144:147], v[112:115]
	v_mfma_f32_16x16x32_bf16 v[104:107], v[176:179], v[152:155], v[104:107]
	v_mfma_f32_16x16x32_bf16 v[96:99], v[200:203], v[152:155], v[96:99]
	v_mfma_f32_16x16x32_bf16 v[88:91], v[176:179], v[160:163], v[88:91]
	v_mfma_f32_16x16x32_bf16 v[80:83], v[200:203], v[160:163], v[80:83]
	v_mfma_f32_16x16x32_bf16 v[72:75], v[176:179], v[168:171], v[72:75]
	v_mfma_f32_16x16x32_bf16 v[64:67], v[200:203], v[168:171], v[64:67]
	v_mfma_f32_16x16x32_bf16 v[120:123], v[196:199], v[148:151], v[120:123]
	v_mfma_f32_16x16x32_bf16 v[112:115], v[204:207], v[148:151], v[112:115]
	v_mfma_f32_16x16x32_bf16 v[104:107], v[196:199], v[156:159], v[104:107]
	v_mfma_f32_16x16x32_bf16 v[96:99], v[204:207], v[156:159], v[96:99]
	v_mfma_f32_16x16x32_bf16 v[88:91], v[196:199], v[164:167], v[88:91]
	v_mfma_f32_16x16x32_bf16 v[80:83], v[204:207], v[164:167], v[80:83]
	v_mfma_f32_16x16x32_bf16 v[72:75], v[196:199], v[172:175], v[72:75]
	v_mfma_f32_16x16x32_bf16 v[64:67], v[204:207], v[172:175], v[64:67]
	s_mov_b32 m0, s8
	v_lshl_add_u64 v[208:209], v[212:213], 0, s[96:97]
	s_barrier
	global_load_lds_dwordx4 v[208:209], off
	v_lshl_add_u64 v[208:209], v[214:215], 0, s[96:97]
	s_mov_b32 m0, s9
	s_nop 0
	global_load_lds_dwordx4 v[208:209], off
	ds_read_b128 v[144:147], v239 offset:49152
	ds_read_b128 v[148:151], v239 offset:50176
	ds_read_b128 v[152:155], v239 offset:51200
	ds_read_b128 v[156:159], v239 offset:52224
	ds_read_b128 v[160:163], v239 offset:53248
	ds_read_b128 v[164:167], v239 offset:54272
	ds_read_b128 v[168:171], v239 offset:55296
	ds_read_b128 v[172:175], v239 offset:56320
	s_barrier
	s_waitcnt lgkmcnt(0)
	s_waitcnt lgkmcnt(0)
	v_mfma_f32_16x16x32_bf16 v[60:63], v[128:131], v[144:147], v[60:63]
	v_mfma_f32_16x16x32_bf16 v[52:55], v[136:139], v[144:147], v[52:55]
	v_mfma_f32_16x16x32_bf16 v[44:47], v[128:131], v[152:155], v[44:47]
	v_mfma_f32_16x16x32_bf16 v[36:39], v[136:139], v[152:155], v[36:39]
	v_mfma_f32_16x16x32_bf16 v[28:31], v[128:131], v[160:163], v[28:31]
	v_mfma_f32_16x16x32_bf16 v[20:23], v[136:139], v[160:163], v[20:23]
	v_mfma_f32_16x16x32_bf16 v[12:15], v[128:131], v[168:171], v[12:15]
	v_mfma_f32_16x16x32_bf16 v[4:7], v[136:139], v[168:171], v[4:7]
	v_mfma_f32_16x16x32_bf16 v[60:63], v[132:135], v[148:151], v[60:63]
	v_mfma_f32_16x16x32_bf16 v[52:55], v[140:143], v[148:151], v[52:55]
	v_mfma_f32_16x16x32_bf16 v[44:47], v[132:135], v[156:159], v[44:47]
	v_mfma_f32_16x16x32_bf16 v[36:39], v[140:143], v[156:159], v[36:39]
	v_mfma_f32_16x16x32_bf16 v[28:31], v[132:135], v[164:167], v[28:31]
	v_mfma_f32_16x16x32_bf16 v[20:23], v[140:143], v[164:167], v[20:23]
	v_mfma_f32_16x16x32_bf16 v[12:15], v[132:135], v[172:175], v[12:15]
	v_mfma_f32_16x16x32_bf16 v[4:7], v[140:143], v[172:175], v[4:7]
	s_barrier
	s_add_i32 s40, s40, s33
	v_lshl_add_u64 v[128:129], v[216:217], 0, s[96:97]
	s_mov_b32 m0, s40
	s_nop 0
	global_load_lds_dwordx4 v[128:129], off
	v_lshl_add_u64 v[128:129], v[218:219], 0, s[96:97]
	s_add_i32 m0, s40, 0x2000
	s_nop 0
	global_load_lds_dwordx4 v[128:129], off
	s_waitcnt vmcnt(6)
	s_barrier
	v_mfma_f32_16x16x32_bf16 v[56:59], v[176:179], v[144:147], v[56:59]
	v_mfma_f32_16x16x32_bf16 v[48:51], v[200:203], v[144:147], v[48:51]
	v_mfma_f32_16x16x32_bf16 v[40:43], v[176:179], v[152:155], v[40:43]
	v_mfma_f32_16x16x32_bf16 v[32:35], v[200:203], v[152:155], v[32:35]
	v_mfma_f32_16x16x32_bf16 v[24:27], v[176:179], v[160:163], v[24:27]
	v_mfma_f32_16x16x32_bf16 v[16:19], v[200:203], v[160:163], v[16:19]
	v_mfma_f32_16x16x32_bf16 v[8:11], v[176:179], v[168:171], v[8:11]
	v_mfma_f32_16x16x32_bf16 v[0:3], v[200:203], v[168:171], v[0:3]
	v_mfma_f32_16x16x32_bf16 v[56:59], v[196:199], v[148:151], v[56:59]
	v_mfma_f32_16x16x32_bf16 v[48:51], v[204:207], v[148:151], v[48:51]
	v_mfma_f32_16x16x32_bf16 v[40:43], v[196:199], v[156:159], v[40:43]
	v_mfma_f32_16x16x32_bf16 v[32:35], v[204:207], v[156:159], v[32:35]
	v_mfma_f32_16x16x32_bf16 v[24:27], v[196:199], v[164:167], v[24:27]
	v_mfma_f32_16x16x32_bf16 v[16:19], v[204:207], v[164:167], v[16:19]
	v_mfma_f32_16x16x32_bf16 v[8:11], v[196:199], v[172:175], v[8:11]
	v_mfma_f32_16x16x32_bf16 v[0:3], v[204:207], v[172:175], v[0:3]
	s_add_u32 s0, s0, 0x100
	s_addc_u32 s1, s1, 0
	s_add_u32 s70, s70, 0x100
	s_addc_u32 s71, s71, 0
	s_cmp_ge_u32 s72, s7
	s_mov_b32 s40, s72
	s_barrier
	s_cbranch_scc0 .LBB0_141
	v_lshl_add_u32 v196, s19, 8, v181
	s_cmp_lt_i32 s78, 2
	s_mov_b64 s[0:1], -1
	s_cbranch_scc1 .LBB0_223
	s_cmp_gt_i32 s78, 2
	s_cbranch_scc0 .LBB0_220
	s_lshl_b32 s0, s18, 8
	s_ashr_i32 s68, s18, 1
	s_and_b32 s0, s0, 0x100
	s_cmp_lt_i32 s68, 2
	v_or_b32_e32 v148, s0, v238
	s_cselect_b64 s[0:1], -1, 0
	s_lshl_b32 s40, s68, 9
	s_add_i32 s80, s40, 0xfffffc00
	v_readlane_b32 s48, v241, 0
	s_lshl_b64 s[70:71], s[80:81], 2
	v_readlane_b32 s62, v241, 14
	v_readlane_b32 s63, v241, 15
	s_add_u32 s69, s62, s70
	s_addc_u32 s80, s63, s71
	s_ashr_i32 s41, s40, 31
	v_readlane_b32 s58, v241, 10
	s_lshl_b64 s[40:41], s[40:41], 2
	v_readlane_b32 s59, v241, 11
	s_add_u32 s99, s58, s40
	s_mov_b32 s83, s82
	s_addc_u32 s82, s59, s41
	s_cmp_lt_i32 s68, 4
	s_cselect_b64 s[72:73], -1, 0
	s_cmp_gt_i32 s68, 3
	s_cselect_b64 s[70:71], -1, 0
	v_mov_b32_e32 v132, 0
	s_and_b64 vcc, exec, s[70:71]
	v_lshlrev_b32_e32 v136, 2, v148
	v_mov_b32_e32 v140, 0
	v_mov_b32_e32 v141, v132
	v_mov_b32_e32 v142, 0
	v_mov_b32_e32 v143, 0
	v_readlane_b32 s49, v241, 1
	v_readlane_b32 s50, v241, 2
	v_readlane_b32 s51, v241, 3
	v_readlane_b32 s52, v241, 4
	v_readlane_b32 s53, v241, 5
	v_readlane_b32 s54, v241, 6
	v_readlane_b32 s55, v241, 7
	v_readlane_b32 s56, v241, 8
	v_readlane_b32 s57, v241, 9
	v_readlane_b32 s60, v241, 12
	v_readlane_b32 s61, v241, 13
	s_cbranch_vccnz .LBB0_146
	s_and_b64 s[40:41], s[0:1], exec
	s_cselect_b32 s41, s82, s80
	s_cselect_b32 s40, s99, s69
	global_load_dwordx4 v[140:143], v136, s[40:41]
